# P6 final output stores write whole 32-byte sectors: the n=0 / n=1 register groups trade lane rows (v_permlane16_swap) before the f32 stores
# baseline (speedup 1.0000x reference)
;     __device__ __forceinline__ void operator()(const f32x4 (&acc)[2][2][4][2], const Unit& u, int wr, int wc, int fr, int fq) const {
;         const int col0 = u.pn * BM + wc * 32 + 8 * fq;
;         if constexpr (BASE_BF16) {
;             u32x4 raw[2][4][2];
; #pragma unroll
;             for (int ai = 0; ai < 2; ++ai)
; #pragma unroll
;                 for (int m = 0; m < 4; ++m) { const int row = u.pm * BM + ai * HALF + wr * 64 + m * 16 + fr; const size_t off = (size_t)row * ldc + col0;
; #pragma unroll
;                     for (int bj = 0; bj < 2; ++bj) raw[ai][m][bj] = *(const u32x4*)((const bf16_t*)base + off + bj * HALF); }
;             asm volatile("" ::: "memory");
; #pragma unroll
;             for (int ai = 0; ai < 2; ++ai)
; #pragma unroll
;                 for (int m = 0; m < 4; ++m) { const int row = u.pm * BM + ai * HALF + wr * 64 + m * 16 + fr; const size_t off = (size_t)row * ldc + col0; float s = 0.f;
; #pragma unroll
;                     for (int bj = 0; bj < 2; ++bj) { const u32x4 r = raw[ai][m][bj];
;                         const f32x4 b0 = {__uint_as_float(r.x << 16), __uint_as_float(r.x & 0xffff0000u), __uint_as_float(r.y << 16), __uint_as_float(r.y & 0xffff0000u)};
;                         const f32x4 b1 = {__uint_as_float(r.z << 16), __uint_as_float(r.z & 0xffff0000u), __uint_as_float(r.w << 16), __uint_as_float(r.w & 0xffff0000u)};
;                         tail(b0, b1, acc[ai][bj][m][0], acc[ai][bj][m][1], out + off + bj * HALF, s); }
; __global__ void __launch_bounds__(NWAVES * 64, 2) hybrid_fwd(Args args) {
;     ...
;             for (int q = 0; q < 4; ++q) { const v2u* xr = (const v2u*)(MIXED + (size_t)(m0 + q) * DM) + lane; rs[q] = __builtin_amdgcn_rsqf(SS2[m0 + q] * (1.f / DM) + NORM_EPS);
; #pragma unroll
;                 for (int j = 0; j < 8; ++j) r[q][j] = xr[64 * j]; }
; #pragma unroll
;             for (int q = 0; q < 4; ++q) { f32x4* orow = (f32x4*)(out + (size_t)(m0 + q) * DM) + lane;
; #pragma unroll
;                 for (int j = 0; j < 8; ++j) { const f32x4 w = wfin[j]; const float s = rs[q];
;                     orow[64 * j] = (f32x4){__uint_as_float(r[q][j].x << 16) * s * w.x, __uint_as_float(r[q][j].x & 0xffff0000u) * s * w.y, __uint_as_float(r[q][j].y << 16) * s * w.z, __uint_as_float(r[q][j].y & 0xffff0000u) * s * w.w}; } }
.Lp6_kdone:
	s_waitcnt lgkmcnt(0)
	s_nop 7
	s_nop 7
	v_and_b32_e32 v254, 63, v185
	v_and_b32_e32 v255, 15, v254
	v_lshrrev_b32_e32 v234, 4, v254
	s_lshl_b32 s40, s37, 6
	v_add_u32_e32 v255, s40, v255
	v_lshlrev_b32_e32 v230, 2, v255
	v_lshlrev_b32_e32 v228, 12, v255
	v_lshlrev_b32_e32 v229, 13, v255
	s_lshl_b32 s41, s38, 6
	v_lshl_add_u32 v228, v234, 4, v228
	v_add_u32_e32 v228, s41, v228
	s_lshl_b32 s41, s38, 7
	v_lshrrev_b32_e32 v186, 1, v234
	v_lshl_add_u32 v229, v186, 6, v229
	v_and_b32_e32 v186, 1, v234
	v_lshl_add_u32 v229, v186, 4, v229
	v_add_u32_e32 v229, s41, v229
	v_mov_b32_e32 v231, 0x358637bd
	v_xor_b32_e32 v232, 16, v254
	v_lshlrev_b32_e32 v232, 2, v232
	v_xor_b32_e32 v233, 32, v254
	v_lshlrev_b32_e32 v233, 2, v233
	s_lshl_b32 s40, s17, 20
	s_lshl_b32 s41, s18, 9
	s_add_u32 s40, s40, s41
	s_add_u32 s48, s76, 0x6800000
	s_addc_u32 s49, s77, 0
	s_add_u32 s48, s48, s40
	s_addc_u32 s49, s49, 0
	s_lshl_b32 s40, s17, 10
	s_add_u32 s40, s40, 0x10000
	s_add_u32 s50, s76, s40
	s_addc_u32 s51, s77, 0
	v_readlane_b32 s52, v244, 2
	v_readlane_b32 s53, v244, 3
	s_lshl_b32 s40, s17, 21
	s_lshl_b32 s41, s18, 10
	s_add_u32 s40, s40, s41
	s_add_u32 s52, s52, s40
	s_addc_u32 s53, s53, 0
	s_lshl_b32 s40, s17, 6
	s_add_u32 s40, s40, 0x28000
	s_add_u32 s54, s76, s40
	s_addc_u32 s55, s77, 0
	v_add_u32_e32 v234, 0x0, v228
	global_load_dwordx4 v[128:131], v234, s[48:49] offset:0
	global_load_dwordx4 v[132:135], v234, s[48:49] offset:256
	v_add_u32_e32 v234, 0x10000, v228
	global_load_dwordx4 v[136:139], v234, s[48:49] offset:0
	global_load_dwordx4 v[140:143], v234, s[48:49] offset:256
	v_add_u32_e32 v234, 0x20000, v228
	global_load_dwordx4 v[144:147], v234, s[48:49] offset:0
	global_load_dwordx4 v[148:151], v234, s[48:49] offset:256
	v_add_u32_e32 v234, 0x30000, v228
	global_load_dwordx4 v[152:155], v234, s[48:49] offset:0
	global_load_dwordx4 v[156:159], v234, s[48:49] offset:256
	v_add_u32_e32 v234, 0x80000, v228
	global_load_dwordx4 v[160:163], v234, s[48:49] offset:0
	global_load_dwordx4 v[164:167], v234, s[48:49] offset:256
	v_add_u32_e32 v234, 0x90000, v228
	global_load_dwordx4 v[168:171], v234, s[48:49] offset:0
	global_load_dwordx4 v[172:175], v234, s[48:49] offset:256
	v_add_u32_e32 v234, 0xa0000, v228
	global_load_dwordx4 v[176:179], v234, s[48:49] offset:0
	global_load_dwordx4 v[180:183], v234, s[48:49] offset:256
	v_add_u32_e32 v234, 0xb0000, v228
	global_load_dwordx4 v[188:191], v234, s[48:49] offset:0
	global_load_dwordx4 v[192:195], v234, s[48:49] offset:256
	s_waitcnt vmcnt(0)
	v_lshlrev_b32_e32 v254, 16, v128
	v_and_b32_e32 v255, 0xffff0000, v128
	v_add_f32_e32 v0, v0, v254
	v_add_f32_e32 v1, v1, v255
	v_mul_f32_e32 v238, v0, v0
	v_fmac_f32_e32 v238, v1, v1
	v_lshlrev_b32_e32 v254, 16, v129
	v_and_b32_e32 v255, 0xffff0000, v129
	v_add_f32_e32 v2, v2, v254
	v_add_f32_e32 v3, v3, v255
	v_fmac_f32_e32 v238, v2, v2
	v_fmac_f32_e32 v238, v3, v3
	v_lshlrev_b32_e32 v254, 16, v130
	v_and_b32_e32 v255, 0xffff0000, v130
	v_add_f32_e32 v4, v4, v254
	v_add_f32_e32 v5, v5, v255
	v_fmac_f32_e32 v238, v4, v4
	v_fmac_f32_e32 v238, v5, v5
	v_lshlrev_b32_e32 v254, 16, v131
	v_and_b32_e32 v255, 0xffff0000, v131
	v_add_f32_e32 v6, v6, v254
	v_add_f32_e32 v7, v7, v255
	v_fmac_f32_e32 v238, v6, v6
	v_fmac_f32_e32 v238, v7, v7
	v_lshlrev_b32_e32 v254, 16, v132
	v_and_b32_e32 v255, 0xffff0000, v132
	v_add_f32_e32 v32, v32, v254
	v_add_f32_e32 v33, v33, v255
	v_fmac_f32_e32 v238, v32, v32
	v_fmac_f32_e32 v238, v33, v33
	v_lshlrev_b32_e32 v254, 16, v133
	v_and_b32_e32 v255, 0xffff0000, v133
	v_add_f32_e32 v34, v34, v254
	v_add_f32_e32 v35, v35, v255
	v_fmac_f32_e32 v238, v34, v34
	v_fmac_f32_e32 v238, v35, v35
	v_lshlrev_b32_e32 v254, 16, v134
	v_and_b32_e32 v255, 0xffff0000, v134
	v_add_f32_e32 v36, v36, v254
	v_add_f32_e32 v37, v37, v255
	v_fmac_f32_e32 v238, v36, v36
	v_fmac_f32_e32 v238, v37, v37
	v_lshlrev_b32_e32 v254, 16, v135
	v_and_b32_e32 v255, 0xffff0000, v135
	v_add_f32_e32 v38, v38, v254
	v_add_f32_e32 v39, v39, v255
	v_fmac_f32_e32 v238, v38, v38
	v_fmac_f32_e32 v238, v39, v39
	v_lshlrev_b32_e32 v254, 16, v136
	v_and_b32_e32 v255, 0xffff0000, v136
	v_add_f32_e32 v8, v8, v254
	v_add_f32_e32 v9, v9, v255
	v_mul_f32_e32 v239, v8, v8
	v_fmac_f32_e32 v239, v9, v9
	v_lshlrev_b32_e32 v254, 16, v137
	v_and_b32_e32 v255, 0xffff0000, v137
	v_add_f32_e32 v10, v10, v254
	v_add_f32_e32 v11, v11, v255
	v_fmac_f32_e32 v239, v10, v10
	v_fmac_f32_e32 v239, v11, v11
	v_lshlrev_b32_e32 v254, 16, v138
	v_and_b32_e32 v255, 0xffff0000, v138
	v_add_f32_e32 v12, v12, v254
	v_add_f32_e32 v13, v13, v255
	v_fmac_f32_e32 v239, v12, v12
	v_fmac_f32_e32 v239, v13, v13
	v_lshlrev_b32_e32 v254, 16, v139
	v_and_b32_e32 v255, 0xffff0000, v139
	v_add_f32_e32 v14, v14, v254
	v_add_f32_e32 v15, v15, v255
	v_fmac_f32_e32 v239, v14, v14
	v_fmac_f32_e32 v239, v15, v15
	v_lshlrev_b32_e32 v254, 16, v140
	v_and_b32_e32 v255, 0xffff0000, v140
	v_add_f32_e32 v40, v40, v254
	v_add_f32_e32 v41, v41, v255
	v_fmac_f32_e32 v239, v40, v40
	v_fmac_f32_e32 v239, v41, v41
	v_lshlrev_b32_e32 v254, 16, v141
	v_and_b32_e32 v255, 0xffff0000, v141
	v_add_f32_e32 v42, v42, v254
	v_add_f32_e32 v43, v43, v255
	v_fmac_f32_e32 v239, v42, v42
	v_fmac_f32_e32 v239, v43, v43
	v_lshlrev_b32_e32 v254, 16, v142
	v_and_b32_e32 v255, 0xffff0000, v142
	v_add_f32_e32 v44, v44, v254
	v_add_f32_e32 v45, v45, v255
	v_fmac_f32_e32 v239, v44, v44
	v_fmac_f32_e32 v239, v45, v45
	v_lshlrev_b32_e32 v254, 16, v143
	v_and_b32_e32 v255, 0xffff0000, v143
	v_add_f32_e32 v46, v46, v254
	v_add_f32_e32 v47, v47, v255
	v_fmac_f32_e32 v239, v46, v46
	v_fmac_f32_e32 v239, v47, v47
	v_lshlrev_b32_e32 v254, 16, v144
;     __device__ __forceinline__ void tail(const f32x4& b0, const f32x4& b1, const f32x4& a0, const f32x4& a1, bf16_t* dst, float& s) const {
;         const f32x4 o0 = b0 + a0, o1 = b1 + a1;
;         s += ((o0[0] * o0[0] + o0[1] * o0[1]) + (o0[2] * o0[2] + o0[3] * o0[3])) + ((o1[0] * o1[0] + o1[1] * o1[1]) + (o1[2] * o1[2] + o1[3] * o1[3]));
;     __device__ __forceinline__ void operator()(const f32x4 (&acc)[2][2][4][2], const Unit& u, int wr, int wc, int fr, int fq) const {
;     ...
;                 for (int m = 0; m < 4; ++m) { const int row = u.pm * BM + ai * HALF + wr * 64 + m * 16 + fr; const size_t off = (size_t)row * ldc + col0; float s = 0.f;
; #pragma unroll
;                     for (int bj = 0; bj < 2; ++bj) { const u32x4 r = raw[ai][m][bj];
;                         const f32x4 b0 = {__uint_as_float(r.x << 16), __uint_as_float(r.x & 0xffff0000u), __uint_as_float(r.y << 16), __uint_as_float(r.y & 0xffff0000u)};
;                         const f32x4 b1 = {__uint_as_float(r.z << 16), __uint_as_float(r.z & 0xffff0000u), __uint_as_float(r.w << 16), __uint_as_float(r.w & 0xffff0000u)};
;                         tail(b0, b1, acc[ai][bj][m][0], acc[ai][bj][m][1], out + off + bj * HALF, s); }
	v_and_b32_e32 v255, 0xffff0000, v144
	v_add_f32_e32 v16, v16, v254
	v_add_f32_e32 v17, v17, v255
	v_mul_f32_e32 v240, v16, v16
	v_fmac_f32_e32 v240, v17, v17
	v_lshlrev_b32_e32 v254, 16, v145
	v_and_b32_e32 v255, 0xffff0000, v145
	v_add_f32_e32 v18, v18, v254
	v_add_f32_e32 v19, v19, v255
	v_fmac_f32_e32 v240, v18, v18
	v_fmac_f32_e32 v240, v19, v19
	v_lshlrev_b32_e32 v254, 16, v146
	v_and_b32_e32 v255, 0xffff0000, v146
	v_add_f32_e32 v20, v20, v254
	v_add_f32_e32 v21, v21, v255
	v_fmac_f32_e32 v240, v20, v20
	v_fmac_f32_e32 v240, v21, v21
	v_lshlrev_b32_e32 v254, 16, v147
	v_and_b32_e32 v255, 0xffff0000, v147
	v_add_f32_e32 v22, v22, v254
	v_add_f32_e32 v23, v23, v255
	v_fmac_f32_e32 v240, v22, v22
	v_fmac_f32_e32 v240, v23, v23
	v_lshlrev_b32_e32 v254, 16, v148
	v_and_b32_e32 v255, 0xffff0000, v148
	v_add_f32_e32 v48, v48, v254
	v_add_f32_e32 v49, v49, v255
	v_fmac_f32_e32 v240, v48, v48
	v_fmac_f32_e32 v240, v49, v49
	v_lshlrev_b32_e32 v254, 16, v149
	v_and_b32_e32 v255, 0xffff0000, v149
	v_add_f32_e32 v50, v50, v254
	v_add_f32_e32 v51, v51, v255
	v_fmac_f32_e32 v240, v50, v50
	v_fmac_f32_e32 v240, v51, v51
	v_lshlrev_b32_e32 v254, 16, v150
	v_and_b32_e32 v255, 0xffff0000, v150
	v_add_f32_e32 v52, v52, v254
	v_add_f32_e32 v53, v53, v255
	v_fmac_f32_e32 v240, v52, v52
	v_fmac_f32_e32 v240, v53, v53
	v_lshlrev_b32_e32 v254, 16, v151
	v_and_b32_e32 v255, 0xffff0000, v151
	v_add_f32_e32 v54, v54, v254
	v_add_f32_e32 v55, v55, v255
	v_fmac_f32_e32 v240, v54, v54
	v_fmac_f32_e32 v240, v55, v55
	v_lshlrev_b32_e32 v254, 16, v152
	v_and_b32_e32 v255, 0xffff0000, v152
	v_add_f32_e32 v24, v24, v254
	v_add_f32_e32 v25, v25, v255
	v_mul_f32_e32 v241, v24, v24
	v_fmac_f32_e32 v241, v25, v25
	v_lshlrev_b32_e32 v254, 16, v153
	v_and_b32_e32 v255, 0xffff0000, v153
	v_add_f32_e32 v26, v26, v254
	v_add_f32_e32 v27, v27, v255
	v_fmac_f32_e32 v241, v26, v26
	v_fmac_f32_e32 v241, v27, v27
	v_lshlrev_b32_e32 v254, 16, v154
	v_and_b32_e32 v255, 0xffff0000, v154
	v_add_f32_e32 v28, v28, v254
	v_add_f32_e32 v29, v29, v255
	v_fmac_f32_e32 v241, v28, v28
	v_fmac_f32_e32 v241, v29, v29
	v_lshlrev_b32_e32 v254, 16, v155
	v_and_b32_e32 v255, 0xffff0000, v155
	v_add_f32_e32 v30, v30, v254
	v_add_f32_e32 v31, v31, v255
	v_fmac_f32_e32 v241, v30, v30
	v_fmac_f32_e32 v241, v31, v31
	v_lshlrev_b32_e32 v254, 16, v156
	v_and_b32_e32 v255, 0xffff0000, v156
	v_add_f32_e32 v56, v56, v254
	v_add_f32_e32 v57, v57, v255
	v_fmac_f32_e32 v241, v56, v56
	v_fmac_f32_e32 v241, v57, v57
	v_lshlrev_b32_e32 v254, 16, v157
	v_and_b32_e32 v255, 0xffff0000, v157
	v_add_f32_e32 v58, v58, v254
	v_add_f32_e32 v59, v59, v255
	v_fmac_f32_e32 v241, v58, v58
	v_fmac_f32_e32 v241, v59, v59
	v_lshlrev_b32_e32 v254, 16, v158
	v_and_b32_e32 v255, 0xffff0000, v158
	v_add_f32_e32 v60, v60, v254
	v_add_f32_e32 v61, v61, v255
	v_fmac_f32_e32 v241, v60, v60
	v_fmac_f32_e32 v241, v61, v61
	v_lshlrev_b32_e32 v254, 16, v159
	v_and_b32_e32 v255, 0xffff0000, v159
	v_add_f32_e32 v62, v62, v254
	v_add_f32_e32 v63, v63, v255
	v_fmac_f32_e32 v241, v62, v62
	v_fmac_f32_e32 v241, v63, v63
	v_lshlrev_b32_e32 v254, 16, v160
	v_and_b32_e32 v255, 0xffff0000, v160
	v_add_f32_e32 v64, v64, v254
	v_add_f32_e32 v65, v65, v255
	v_mul_f32_e32 v242, v64, v64
	v_fmac_f32_e32 v242, v65, v65
	v_lshlrev_b32_e32 v254, 16, v161
	v_and_b32_e32 v255, 0xffff0000, v161
	v_add_f32_e32 v66, v66, v254
	v_add_f32_e32 v67, v67, v255
	v_fmac_f32_e32 v242, v66, v66
	v_fmac_f32_e32 v242, v67, v67
	v_lshlrev_b32_e32 v254, 16, v162
	v_and_b32_e32 v255, 0xffff0000, v162
	v_add_f32_e32 v68, v68, v254
	v_add_f32_e32 v69, v69, v255
	v_fmac_f32_e32 v242, v68, v68
	v_fmac_f32_e32 v242, v69, v69
	v_lshlrev_b32_e32 v254, 16, v163
	v_and_b32_e32 v255, 0xffff0000, v163
	v_add_f32_e32 v70, v70, v254
	v_add_f32_e32 v71, v71, v255
	v_fmac_f32_e32 v242, v70, v70
	v_fmac_f32_e32 v242, v71, v71
	v_lshlrev_b32_e32 v254, 16, v164
	v_and_b32_e32 v255, 0xffff0000, v164
	v_add_f32_e32 v96, v96, v254
	v_add_f32_e32 v97, v97, v255
	v_fmac_f32_e32 v242, v96, v96
	v_fmac_f32_e32 v242, v97, v97
	v_lshlrev_b32_e32 v254, 16, v165
	v_and_b32_e32 v255, 0xffff0000, v165
	v_add_f32_e32 v98, v98, v254
	v_add_f32_e32 v99, v99, v255
	v_fmac_f32_e32 v242, v98, v98
	v_fmac_f32_e32 v242, v99, v99
	v_lshlrev_b32_e32 v254, 16, v166
	v_and_b32_e32 v255, 0xffff0000, v166
	v_add_f32_e32 v100, v100, v254
	v_add_f32_e32 v101, v101, v255
	v_fmac_f32_e32 v242, v100, v100
	v_fmac_f32_e32 v242, v101, v101
	v_lshlrev_b32_e32 v254, 16, v167
	v_and_b32_e32 v255, 0xffff0000, v167
	v_add_f32_e32 v102, v102, v254
	v_add_f32_e32 v103, v103, v255
	v_fmac_f32_e32 v242, v102, v102
	v_fmac_f32_e32 v242, v103, v103
	v_lshlrev_b32_e32 v254, 16, v168
	v_and_b32_e32 v255, 0xffff0000, v168
	v_add_f32_e32 v72, v72, v254
	v_add_f32_e32 v73, v73, v255
	v_mul_f32_e32 v243, v72, v72
	v_fmac_f32_e32 v243, v73, v73
	v_lshlrev_b32_e32 v254, 16, v169
	v_and_b32_e32 v255, 0xffff0000, v169
	v_add_f32_e32 v74, v74, v254
	v_add_f32_e32 v75, v75, v255
	v_fmac_f32_e32 v243, v74, v74
	v_fmac_f32_e32 v243, v75, v75
	v_lshlrev_b32_e32 v254, 16, v170
	v_and_b32_e32 v255, 0xffff0000, v170
	v_add_f32_e32 v76, v76, v254
	v_add_f32_e32 v77, v77, v255
	v_fmac_f32_e32 v243, v76, v76
	v_fmac_f32_e32 v243, v77, v77
	v_lshlrev_b32_e32 v254, 16, v171
	v_and_b32_e32 v255, 0xffff0000, v171
	v_add_f32_e32 v78, v78, v254
	v_add_f32_e32 v79, v79, v255
	v_fmac_f32_e32 v243, v78, v78
	v_fmac_f32_e32 v243, v79, v79
	v_lshlrev_b32_e32 v254, 16, v172
	v_and_b32_e32 v255, 0xffff0000, v172
	v_add_f32_e32 v104, v104, v254
	v_add_f32_e32 v105, v105, v255
	v_fmac_f32_e32 v243, v104, v104
	v_fmac_f32_e32 v243, v105, v105
	v_lshlrev_b32_e32 v254, 16, v173
;     __device__ __forceinline__ void tail(const f32x4& b0, const f32x4& b1, const f32x4& a0, const f32x4& a1, bf16_t* dst, float& s) const {
;         const f32x4 o0 = b0 + a0, o1 = b1 + a1;
;         s += ((o0[0] * o0[0] + o0[1] * o0[1]) + (o0[2] * o0[2] + o0[3] * o0[3])) + ((o1[0] * o1[0] + o1[1] * o1[1]) + (o1[2] * o1[2] + o1[3] * o1[3]));
;         u32x4 w; w.x = cvt_pk_bf16(o0[0], o0[1]); w.y = cvt_pk_bf16(o0[2], o0[3]); w.z = cvt_pk_bf16(o1[0], o1[1]); w.w = cvt_pk_bf16(o1[2], o1[3]);
;         *(u32x4*)dst = w;
;     }
;     __device__ __forceinline__ void operator()(const f32x4 (&acc)[2][2][4][2], const Unit& u, int wr, int wc, int fr, int fq) const {
;         const int col0 = u.pn * BM + wc * 32 + 8 * fq;
;         if constexpr (BASE_BF16) {
;             u32x4 raw[2][4][2];
; #pragma unroll
;             for (int ai = 0; ai < 2; ++ai)
; #pragma unroll
;                 for (int m = 0; m < 4; ++m) { const int row = u.pm * BM + ai * HALF + wr * 64 + m * 16 + fr; const size_t off = (size_t)row * ldc + col0;
; #pragma unroll
;                     for (int bj = 0; bj < 2; ++bj) raw[ai][m][bj] = *(const u32x4*)((const bf16_t*)base + off + bj * HALF); }
;             asm volatile("" ::: "memory");
; #pragma unroll
;             for (int ai = 0; ai < 2; ++ai)
; #pragma unroll
;                 for (int m = 0; m < 4; ++m) { const int row = u.pm * BM + ai * HALF + wr * 64 + m * 16 + fr; const size_t off = (size_t)row * ldc + col0; float s = 0.f;
; #pragma unroll
;                     for (int bj = 0; bj < 2; ++bj) { const u32x4 r = raw[ai][m][bj];
;                         const f32x4 b0 = {__uint_as_float(r.x << 16), __uint_as_float(r.x & 0xffff0000u), __uint_as_float(r.y << 16), __uint_as_float(r.y & 0xffff0000u)};
;                         const f32x4 b1 = {__uint_as_float(r.z << 16), __uint_as_float(r.z & 0xffff0000u), __uint_as_float(r.w << 16), __uint_as_float(r.w & 0xffff0000u)};
;                         tail(b0, b1, acc[ai][bj][m][0], acc[ai][bj][m][1], out + off + bj * HALF, s); }
;                     s += __shfl_xor(s, 16); s += __shfl_xor(s, 32);
;                     if (fq == 0) atomicAdd(ss + row, s); }
; __global__ void __launch_bounds__(NWAVES * 64, 2) hybrid_fwd(Args args) {
;     ...
;         f32x4 wfin[8];
; #pragma unroll
;         for (int j = 0; j < 8; ++j) wfin[j] = ((const f32x4*)norm_final_w + lane)[64 * j];
	v_and_b32_e32 v255, 0xffff0000, v173
	v_add_f32_e32 v106, v106, v254
	v_add_f32_e32 v107, v107, v255
	v_fmac_f32_e32 v243, v106, v106
	v_fmac_f32_e32 v243, v107, v107
	v_lshlrev_b32_e32 v254, 16, v174
	v_and_b32_e32 v255, 0xffff0000, v174
	v_add_f32_e32 v108, v108, v254
	v_add_f32_e32 v109, v109, v255
	v_fmac_f32_e32 v243, v108, v108
	v_fmac_f32_e32 v243, v109, v109
	v_lshlrev_b32_e32 v254, 16, v175
	v_and_b32_e32 v255, 0xffff0000, v175
	v_add_f32_e32 v110, v110, v254
	v_add_f32_e32 v111, v111, v255
	v_fmac_f32_e32 v243, v110, v110
	v_fmac_f32_e32 v243, v111, v111
	v_lshlrev_b32_e32 v254, 16, v176
	v_and_b32_e32 v255, 0xffff0000, v176
	v_add_f32_e32 v80, v80, v254
	v_add_f32_e32 v81, v81, v255
	v_mul_f32_e32 v226, v80, v80
	v_fmac_f32_e32 v226, v81, v81
	v_lshlrev_b32_e32 v254, 16, v177
	v_and_b32_e32 v255, 0xffff0000, v177
	v_add_f32_e32 v82, v82, v254
	v_add_f32_e32 v83, v83, v255
	v_fmac_f32_e32 v226, v82, v82
	v_fmac_f32_e32 v226, v83, v83
	v_lshlrev_b32_e32 v254, 16, v178
	v_and_b32_e32 v255, 0xffff0000, v178
	v_add_f32_e32 v84, v84, v254
	v_add_f32_e32 v85, v85, v255
	v_fmac_f32_e32 v226, v84, v84
	v_fmac_f32_e32 v226, v85, v85
	v_lshlrev_b32_e32 v254, 16, v179
	v_and_b32_e32 v255, 0xffff0000, v179
	v_add_f32_e32 v86, v86, v254
	v_add_f32_e32 v87, v87, v255
	v_fmac_f32_e32 v226, v86, v86
	v_fmac_f32_e32 v226, v87, v87
	v_lshlrev_b32_e32 v254, 16, v180
	v_and_b32_e32 v255, 0xffff0000, v180
	v_add_f32_e32 v112, v112, v254
	v_add_f32_e32 v113, v113, v255
	v_fmac_f32_e32 v226, v112, v112
	v_fmac_f32_e32 v226, v113, v113
	v_lshlrev_b32_e32 v254, 16, v181
	v_and_b32_e32 v255, 0xffff0000, v181
	v_add_f32_e32 v114, v114, v254
	v_add_f32_e32 v115, v115, v255
	v_fmac_f32_e32 v226, v114, v114
	v_fmac_f32_e32 v226, v115, v115
	v_lshlrev_b32_e32 v254, 16, v182
	v_and_b32_e32 v255, 0xffff0000, v182
	v_add_f32_e32 v116, v116, v254
	v_add_f32_e32 v117, v117, v255
	v_fmac_f32_e32 v226, v116, v116
	v_fmac_f32_e32 v226, v117, v117
	v_lshlrev_b32_e32 v254, 16, v183
	v_and_b32_e32 v255, 0xffff0000, v183
	v_add_f32_e32 v118, v118, v254
	v_add_f32_e32 v119, v119, v255
	v_fmac_f32_e32 v226, v118, v118
	v_fmac_f32_e32 v226, v119, v119
	v_lshlrev_b32_e32 v254, 16, v188
	v_and_b32_e32 v255, 0xffff0000, v188
	v_add_f32_e32 v88, v88, v254
	v_add_f32_e32 v89, v89, v255
	v_mul_f32_e32 v227, v88, v88
	v_fmac_f32_e32 v227, v89, v89
	v_lshlrev_b32_e32 v254, 16, v189
	v_and_b32_e32 v255, 0xffff0000, v189
	v_add_f32_e32 v90, v90, v254
	v_add_f32_e32 v91, v91, v255
	v_fmac_f32_e32 v227, v90, v90
	v_fmac_f32_e32 v227, v91, v91
	v_lshlrev_b32_e32 v254, 16, v190
	v_and_b32_e32 v255, 0xffff0000, v190
	v_add_f32_e32 v92, v92, v254
	v_add_f32_e32 v93, v93, v255
	v_fmac_f32_e32 v227, v92, v92
	v_fmac_f32_e32 v227, v93, v93
	v_lshlrev_b32_e32 v254, 16, v191
	v_and_b32_e32 v255, 0xffff0000, v191
	v_add_f32_e32 v94, v94, v254
	v_add_f32_e32 v95, v95, v255
	v_fmac_f32_e32 v227, v94, v94
	v_fmac_f32_e32 v227, v95, v95
	v_lshlrev_b32_e32 v254, 16, v192
	v_and_b32_e32 v255, 0xffff0000, v192
	v_add_f32_e32 v120, v120, v254
	v_add_f32_e32 v121, v121, v255
	v_fmac_f32_e32 v227, v120, v120
	v_fmac_f32_e32 v227, v121, v121
	v_lshlrev_b32_e32 v254, 16, v193
	v_and_b32_e32 v255, 0xffff0000, v193
	v_add_f32_e32 v122, v122, v254
	v_add_f32_e32 v123, v123, v255
	v_fmac_f32_e32 v227, v122, v122
	v_fmac_f32_e32 v227, v123, v123
	v_lshlrev_b32_e32 v254, 16, v194
	v_and_b32_e32 v255, 0xffff0000, v194
	v_add_f32_e32 v124, v124, v254
	v_add_f32_e32 v125, v125, v255
	v_fmac_f32_e32 v227, v124, v124
	v_fmac_f32_e32 v227, v125, v125
	v_lshlrev_b32_e32 v254, 16, v195
	v_and_b32_e32 v255, 0xffff0000, v195
	v_add_f32_e32 v126, v126, v254
	v_add_f32_e32 v127, v127, v255
	v_fmac_f32_e32 v227, v126, v126
	v_fmac_f32_e32 v227, v127, v127
	v_readlane_b32 s44, v244, 0
	v_readlane_b32 s45, v244, 1
	v_and_b32_e32 v254, 63, v185
	v_lshrrev_b32_e32 v254, 4, v254
	v_lshlrev_b32_e32 v254, 5, v254
	s_lshl_b32 s40, s38, 7
	s_lshl_b32 s41, s18, 10
	s_add_u32 s40, s40, s41
	v_add_u32_e32 v254, s40, v254
	global_load_dwordx4 v[160:163], v254, s[44:45] offset:0
	global_load_dwordx4 v[164:167], v254, s[44:45] offset:16
	global_load_dwordx4 v[168:171], v254, s[44:45] offset:512
	global_load_dwordx4 v[172:175], v254, s[44:45] offset:528
	ds_bpermute_b32 v128, v232, v238
	ds_bpermute_b32 v132, v232, v239
	ds_bpermute_b32 v136, v232, v240
	ds_bpermute_b32 v140, v232, v241
	ds_bpermute_b32 v144, v232, v242
	ds_bpermute_b32 v148, v232, v243
	ds_bpermute_b32 v152, v232, v226
	ds_bpermute_b32 v156, v232, v227
	s_waitcnt lgkmcnt(0)
	v_add_f32_e32 v238, v238, v128
	v_add_f32_e32 v239, v239, v132
	v_add_f32_e32 v240, v240, v136
	v_add_f32_e32 v241, v241, v140
	v_add_f32_e32 v242, v242, v144
	v_add_f32_e32 v243, v243, v148
	v_add_f32_e32 v226, v226, v152
	v_add_f32_e32 v227, v227, v156
	ds_bpermute_b32 v128, v233, v238
	ds_bpermute_b32 v132, v233, v239
	ds_bpermute_b32 v136, v233, v240
	ds_bpermute_b32 v140, v233, v241
	ds_bpermute_b32 v144, v233, v242
	ds_bpermute_b32 v148, v233, v243
	ds_bpermute_b32 v152, v233, v226
	ds_bpermute_b32 v156, v233, v227
	s_waitcnt lgkmcnt(0)
	v_add_f32_e32 v238, v238, v128
	v_add_f32_e32 v239, v239, v132
	v_add_f32_e32 v240, v240, v136
	v_add_f32_e32 v241, v241, v140
	v_add_f32_e32 v242, v242, v144
	v_add_f32_e32 v243, v243, v148
	v_add_f32_e32 v226, v226, v152
	v_add_f32_e32 v227, v227, v156
	s_mov_b64 exec, 0xffff
	global_atomic_add_f32 v230, v238, s[50:51] offset:0
	global_atomic_add_f32 v230, v239, s[50:51] offset:64
	global_atomic_add_f32 v230, v240, s[50:51] offset:128
	global_atomic_add_f32 v230, v241, s[50:51] offset:192
	global_atomic_add_f32 v230, v242, s[50:51] offset:512
	global_atomic_add_f32 v230, v243, s[50:51] offset:576
	global_atomic_add_f32 v230, v226, s[50:51] offset:640
	global_atomic_add_f32 v230, v227, s[50:51] offset:704
	s_mov_b64 exec, -1
	s_waitcnt vmcnt(0)
	s_barrier
	s_cmp_lg_u32 s36, 0
	s_cbranch_scc1 .Lp6_fin_arr
	s_mov_b64 exec, 1
	v_mov_b32_e32 v237, 0
	v_mov_b32_e32 v236, 1
	global_atomic_add v237, v236, s[54:55]
	s_mov_b64 exec, -1

; __global__ void __launch_bounds__(NWAVES * 64, 2) hybrid_fwd(Args args) {
;     ...
;         for (int m0 = gw * 4; m0 < M; m0 += NGW * 4) {
;             v2u r[4][8]; float rs[4];
; #pragma unroll
;             for (int q = 0; q < 4; ++q) { const v2u* xr = (const v2u*)(MIXED + (size_t)(m0 + q) * DM) + lane; rs[q] = __builtin_amdgcn_rsqf(SS2[m0 + q] * (1.f / DM) + NORM_EPS);
; #pragma unroll
;                 for (int j = 0; j < 8; ++j) r[q][j] = xr[64 * j]; }
; #pragma unroll
;             for (int q = 0; q < 4; ++q) { f32x4* orow = (f32x4*)(out + (size_t)(m0 + q) * DM) + lane;
; #pragma unroll
;                 for (int j = 0; j < 8; ++j) { const f32x4 w = wfin[j]; const float s = rs[q];
;                     orow[64 * j] = (f32x4){__uint_as_float(r[q][j].x << 16) * s * w.x, __uint_as_float(r[q][j].x & 0xffff0000u) * s * w.y, __uint_as_float(r[q][j].y << 16) * s * w.z, __uint_as_float(r[q][j].y & 0xffff0000u) * s * w.w}; } }
.Lp6_fin_wait:
	s_barrier
	global_load_dword v238, v230, s[50:51] offset:0 sc0 sc1
	global_load_dword v239, v230, s[50:51] offset:64 sc0 sc1
	global_load_dword v240, v230, s[50:51] offset:128 sc0 sc1
	global_load_dword v241, v230, s[50:51] offset:192 sc0 sc1
	global_load_dword v242, v230, s[50:51] offset:512 sc0 sc1
	global_load_dword v243, v230, s[50:51] offset:576 sc0 sc1
	global_load_dword v226, v230, s[50:51] offset:640 sc0 sc1
	global_load_dword v227, v230, s[50:51] offset:704 sc0 sc1
	s_waitcnt vmcnt(0)
	v_fmamk_f32 v235, v238, 0x3a000000, v231
	v_add_u32_e32 v234, 0x0, v229
	v_rsq_f32_e32 v235, v235
	s_nop 0
	v_mul_f32_e32 v0, v0, v235
	v_mul_f32_e32 v1, v1, v235
	v_mul_f32_e32 v2, v2, v235
	v_mul_f32_e32 v3, v3, v235
	v_mul_f32_e32 v4, v4, v235
	v_mul_f32_e32 v5, v5, v235
	v_mul_f32_e32 v6, v6, v235
	v_mul_f32_e32 v7, v7, v235
	v_mul_f32_e32 v32, v32, v235
	v_mul_f32_e32 v33, v33, v235
	v_mul_f32_e32 v34, v34, v235
	v_mul_f32_e32 v35, v35, v235
	v_mul_f32_e32 v36, v36, v235
	v_mul_f32_e32 v37, v37, v235
	v_mul_f32_e32 v38, v38, v235
	v_mul_f32_e32 v39, v39, v235
	v_mul_f32_e32 v0, v0, v160
	v_mul_f32_e32 v1, v1, v161
	v_mul_f32_e32 v2, v2, v162
	v_mul_f32_e32 v3, v3, v163
	v_mul_f32_e32 v4, v4, v164
	v_mul_f32_e32 v5, v5, v165
	v_mul_f32_e32 v6, v6, v166
	v_mul_f32_e32 v7, v7, v167
	v_mul_f32_e32 v32, v32, v168
	v_mul_f32_e32 v33, v33, v169
	v_mul_f32_e32 v34, v34, v170
	v_mul_f32_e32 v35, v35, v171
	v_mul_f32_e32 v36, v36, v172
	v_mul_f32_e32 v37, v37, v173
	v_mul_f32_e32 v38, v38, v174
	v_mul_f32_e32 v39, v39, v175
	s_nop 1
	v_permlane16_swap_b32_e32 v0, v4
	v_permlane16_swap_b32_e32 v1, v5
	v_permlane16_swap_b32_e32 v2, v6
	v_permlane16_swap_b32_e32 v3, v7
	v_permlane16_swap_b32_e32 v32, v36
	v_permlane16_swap_b32_e32 v33, v37
	v_permlane16_swap_b32_e32 v34, v38
	v_permlane16_swap_b32_e32 v35, v39
	global_store_dwordx4 v234, v[0:3], s[52:53] offset:0
	global_store_dwordx4 v234, v[4:7], s[52:53] offset:32
	global_store_dwordx4 v234, v[32:35], s[52:53] offset:512
	global_store_dwordx4 v234, v[36:39], s[52:53] offset:544
	s_nop 1
	v_fmamk_f32 v235, v239, 0x3a000000, v231
	v_add_u32_e32 v234, 0x20000, v229
	v_rsq_f32_e32 v235, v235
	s_nop 0
	v_mul_f32_e32 v8, v8, v235
	v_mul_f32_e32 v9, v9, v235
	v_mul_f32_e32 v10, v10, v235
	v_mul_f32_e32 v11, v11, v235
	v_mul_f32_e32 v12, v12, v235
	v_mul_f32_e32 v13, v13, v235
	v_mul_f32_e32 v14, v14, v235
	v_mul_f32_e32 v15, v15, v235
	v_mul_f32_e32 v40, v40, v235
	v_mul_f32_e32 v41, v41, v235
	v_mul_f32_e32 v42, v42, v235
	v_mul_f32_e32 v43, v43, v235
	v_mul_f32_e32 v44, v44, v235
	v_mul_f32_e32 v45, v45, v235
	v_mul_f32_e32 v46, v46, v235
	v_mul_f32_e32 v47, v47, v235
	v_mul_f32_e32 v8, v8, v160
	v_mul_f32_e32 v9, v9, v161
	v_mul_f32_e32 v10, v10, v162
	v_mul_f32_e32 v11, v11, v163
	v_mul_f32_e32 v12, v12, v164
	v_mul_f32_e32 v13, v13, v165
	v_mul_f32_e32 v14, v14, v166
	v_mul_f32_e32 v15, v15, v167
	v_mul_f32_e32 v40, v40, v168
	v_mul_f32_e32 v41, v41, v169
	v_mul_f32_e32 v42, v42, v170
	v_mul_f32_e32 v43, v43, v171
	v_mul_f32_e32 v44, v44, v172
	v_mul_f32_e32 v45, v45, v173
	v_mul_f32_e32 v46, v46, v174
	v_mul_f32_e32 v47, v47, v175
	s_nop 1
	v_permlane16_swap_b32_e32 v8, v12
	v_permlane16_swap_b32_e32 v9, v13
	v_permlane16_swap_b32_e32 v10, v14
	v_permlane16_swap_b32_e32 v11, v15
	v_permlane16_swap_b32_e32 v40, v44
	v_permlane16_swap_b32_e32 v41, v45
	v_permlane16_swap_b32_e32 v42, v46
	v_permlane16_swap_b32_e32 v43, v47
	global_store_dwordx4 v234, v[8:11], s[52:53] offset:0
	global_store_dwordx4 v234, v[12:15], s[52:53] offset:32
	global_store_dwordx4 v234, v[40:43], s[52:53] offset:512
	global_store_dwordx4 v234, v[44:47], s[52:53] offset:544
	s_nop 1
	v_fmamk_f32 v235, v240, 0x3a000000, v231
	v_add_u32_e32 v234, 0x40000, v229
	v_rsq_f32_e32 v235, v235
	s_nop 0
	v_mul_f32_e32 v16, v16, v235
	v_mul_f32_e32 v17, v17, v235
	v_mul_f32_e32 v18, v18, v235
	v_mul_f32_e32 v19, v19, v235
	v_mul_f32_e32 v20, v20, v235
	v_mul_f32_e32 v21, v21, v235
	v_mul_f32_e32 v22, v22, v235
	v_mul_f32_e32 v23, v23, v235
	v_mul_f32_e32 v48, v48, v235
	v_mul_f32_e32 v49, v49, v235
	v_mul_f32_e32 v50, v50, v235
	v_mul_f32_e32 v51, v51, v235
	v_mul_f32_e32 v52, v52, v235
	v_mul_f32_e32 v53, v53, v235
	v_mul_f32_e32 v54, v54, v235
	v_mul_f32_e32 v55, v55, v235
	v_mul_f32_e32 v16, v16, v160
	v_mul_f32_e32 v17, v17, v161
	v_mul_f32_e32 v18, v18, v162
	v_mul_f32_e32 v19, v19, v163
	v_mul_f32_e32 v20, v20, v164
	v_mul_f32_e32 v21, v21, v165
	v_mul_f32_e32 v22, v22, v166
	v_mul_f32_e32 v23, v23, v167
	v_mul_f32_e32 v48, v48, v168
	v_mul_f32_e32 v49, v49, v169
	v_mul_f32_e32 v50, v50, v170
	v_mul_f32_e32 v51, v51, v171
	v_mul_f32_e32 v52, v52, v172
	v_mul_f32_e32 v53, v53, v173
	v_mul_f32_e32 v54, v54, v174
	v_mul_f32_e32 v55, v55, v175
	s_nop 1
	v_permlane16_swap_b32_e32 v16, v20
	v_permlane16_swap_b32_e32 v17, v21
	v_permlane16_swap_b32_e32 v18, v22
	v_permlane16_swap_b32_e32 v19, v23
	v_permlane16_swap_b32_e32 v48, v52
	v_permlane16_swap_b32_e32 v49, v53
	v_permlane16_swap_b32_e32 v50, v54
	v_permlane16_swap_b32_e32 v51, v55
	global_store_dwordx4 v234, v[16:19], s[52:53] offset:0
	global_store_dwordx4 v234, v[20:23], s[52:53] offset:32
	global_store_dwordx4 v234, v[48:51], s[52:53] offset:512
	global_store_dwordx4 v234, v[52:55], s[52:53] offset:544
	s_nop 1
	v_fmamk_f32 v235, v241, 0x3a000000, v231
	v_add_u32_e32 v234, 0x60000, v229
	v_rsq_f32_e32 v235, v235
	s_nop 0
	v_mul_f32_e32 v24, v24, v235
	v_mul_f32_e32 v25, v25, v235
	v_mul_f32_e32 v26, v26, v235
	v_mul_f32_e32 v27, v27, v235
	v_mul_f32_e32 v28, v28, v235
	v_mul_f32_e32 v29, v29, v235
	v_mul_f32_e32 v30, v30, v235
	v_mul_f32_e32 v31, v31, v235
; __global__ void __launch_bounds__(NWAVES * 64, 2) hybrid_fwd(Args args) {
;     ...
;             for (int q = 0; q < 4; ++q) { f32x4* orow = (f32x4*)(out + (size_t)(m0 + q) * DM) + lane;
; #pragma unroll
;                 for (int j = 0; j < 8; ++j) { const f32x4 w = wfin[j]; const float s = rs[q];
;                     orow[64 * j] = (f32x4){__uint_as_float(r[q][j].x << 16) * s * w.x, __uint_as_float(r[q][j].x & 0xffff0000u) * s * w.y, __uint_as_float(r[q][j].y << 16) * s * w.z, __uint_as_float(r[q][j].y & 0xffff0000u) * s * w.w}; } }
	v_mul_f32_e32 v56, v56, v235
	v_mul_f32_e32 v57, v57, v235
	v_mul_f32_e32 v58, v58, v235
	v_mul_f32_e32 v59, v59, v235
	v_mul_f32_e32 v60, v60, v235
	v_mul_f32_e32 v61, v61, v235
	v_mul_f32_e32 v62, v62, v235
	v_mul_f32_e32 v63, v63, v235
	v_mul_f32_e32 v24, v24, v160
	v_mul_f32_e32 v25, v25, v161
	v_mul_f32_e32 v26, v26, v162
	v_mul_f32_e32 v27, v27, v163
	v_mul_f32_e32 v28, v28, v164
	v_mul_f32_e32 v29, v29, v165
	v_mul_f32_e32 v30, v30, v166
	v_mul_f32_e32 v31, v31, v167
	v_mul_f32_e32 v56, v56, v168
	v_mul_f32_e32 v57, v57, v169
	v_mul_f32_e32 v58, v58, v170
	v_mul_f32_e32 v59, v59, v171
	v_mul_f32_e32 v60, v60, v172
	v_mul_f32_e32 v61, v61, v173
	v_mul_f32_e32 v62, v62, v174
	v_mul_f32_e32 v63, v63, v175
	s_nop 1
	v_permlane16_swap_b32_e32 v24, v28
	v_permlane16_swap_b32_e32 v25, v29
	v_permlane16_swap_b32_e32 v26, v30
	v_permlane16_swap_b32_e32 v27, v31
	v_permlane16_swap_b32_e32 v56, v60
	v_permlane16_swap_b32_e32 v57, v61
	v_permlane16_swap_b32_e32 v58, v62
	v_permlane16_swap_b32_e32 v59, v63
	global_store_dwordx4 v234, v[24:27], s[52:53] offset:0
	global_store_dwordx4 v234, v[28:31], s[52:53] offset:32
	global_store_dwordx4 v234, v[56:59], s[52:53] offset:512
	global_store_dwordx4 v234, v[60:63], s[52:53] offset:544
	s_nop 1
	v_fmamk_f32 v235, v242, 0x3a000000, v231
	v_add_u32_e32 v234, 0x100000, v229
	v_rsq_f32_e32 v235, v235
	s_nop 0
	v_mul_f32_e32 v64, v64, v235
	v_mul_f32_e32 v65, v65, v235
	v_mul_f32_e32 v66, v66, v235
	v_mul_f32_e32 v67, v67, v235
	v_mul_f32_e32 v68, v68, v235
	v_mul_f32_e32 v69, v69, v235
	v_mul_f32_e32 v70, v70, v235
	v_mul_f32_e32 v71, v71, v235
	v_mul_f32_e32 v96, v96, v235
	v_mul_f32_e32 v97, v97, v235
	v_mul_f32_e32 v98, v98, v235
	v_mul_f32_e32 v99, v99, v235
	v_mul_f32_e32 v100, v100, v235
	v_mul_f32_e32 v101, v101, v235
	v_mul_f32_e32 v102, v102, v235
	v_mul_f32_e32 v103, v103, v235
	v_mul_f32_e32 v64, v64, v160
	v_mul_f32_e32 v65, v65, v161
	v_mul_f32_e32 v66, v66, v162
	v_mul_f32_e32 v67, v67, v163
	v_mul_f32_e32 v68, v68, v164
	v_mul_f32_e32 v69, v69, v165
	v_mul_f32_e32 v70, v70, v166
	v_mul_f32_e32 v71, v71, v167
	v_mul_f32_e32 v96, v96, v168
	v_mul_f32_e32 v97, v97, v169
	v_mul_f32_e32 v98, v98, v170
	v_mul_f32_e32 v99, v99, v171
	v_mul_f32_e32 v100, v100, v172
	v_mul_f32_e32 v101, v101, v173
	v_mul_f32_e32 v102, v102, v174
	v_mul_f32_e32 v103, v103, v175
	s_nop 1
	v_permlane16_swap_b32_e32 v64, v68
	v_permlane16_swap_b32_e32 v65, v69
	v_permlane16_swap_b32_e32 v66, v70
	v_permlane16_swap_b32_e32 v67, v71
	v_permlane16_swap_b32_e32 v96, v100
	v_permlane16_swap_b32_e32 v97, v101
	v_permlane16_swap_b32_e32 v98, v102
	v_permlane16_swap_b32_e32 v99, v103
	global_store_dwordx4 v234, v[64:67], s[52:53] offset:0
	global_store_dwordx4 v234, v[68:71], s[52:53] offset:32
	global_store_dwordx4 v234, v[96:99], s[52:53] offset:512
	global_store_dwordx4 v234, v[100:103], s[52:53] offset:544
	s_nop 1
	v_fmamk_f32 v235, v243, 0x3a000000, v231
	v_add_u32_e32 v234, 0x120000, v229
	v_rsq_f32_e32 v235, v235
	s_nop 0
	v_mul_f32_e32 v72, v72, v235
	v_mul_f32_e32 v73, v73, v235
	v_mul_f32_e32 v74, v74, v235
	v_mul_f32_e32 v75, v75, v235
	v_mul_f32_e32 v76, v76, v235
	v_mul_f32_e32 v77, v77, v235
	v_mul_f32_e32 v78, v78, v235
	v_mul_f32_e32 v79, v79, v235
	v_mul_f32_e32 v104, v104, v235
	v_mul_f32_e32 v105, v105, v235
	v_mul_f32_e32 v106, v106, v235
	v_mul_f32_e32 v107, v107, v235
	v_mul_f32_e32 v108, v108, v235
	v_mul_f32_e32 v109, v109, v235
	v_mul_f32_e32 v110, v110, v235
	v_mul_f32_e32 v111, v111, v235
	v_mul_f32_e32 v72, v72, v160
	v_mul_f32_e32 v73, v73, v161
	v_mul_f32_e32 v74, v74, v162
	v_mul_f32_e32 v75, v75, v163
	v_mul_f32_e32 v76, v76, v164
	v_mul_f32_e32 v77, v77, v165
	v_mul_f32_e32 v78, v78, v166
	v_mul_f32_e32 v79, v79, v167
	v_mul_f32_e32 v104, v104, v168
	v_mul_f32_e32 v105, v105, v169
	v_mul_f32_e32 v106, v106, v170
	v_mul_f32_e32 v107, v107, v171
	v_mul_f32_e32 v108, v108, v172
	v_mul_f32_e32 v109, v109, v173
	v_mul_f32_e32 v110, v110, v174
	v_mul_f32_e32 v111, v111, v175
	s_nop 1
; template <class Epi, class Sched, bool ALIGN_EPI = false, bool SP2 = false>
; __device__ __forceinline__ void gemm_phase(PG8_LAS unsigned char* lds, const Gemm g, const Sched& S, const Epi& E) {
;     ...
;         if (!has_next) break;
; #pragma unroll
;         for (int a = 0; a < 2; ++a)
; #pragma unroll
;             for (int b = 0; b < 2; ++b)
; #pragma unroll
;                 for (int m = 0; m < 4; ++m)
; #pragma unroll
;                     for (int n = 0; n < 2; ++n) acc[a][b][m][n] = (f32x4){0.f, 0.f, 0.f, 0.f};
;         cur = nxt; cA = nA; cB = nB; ++ui;
; __global__ void __launch_bounds__(NWAVES * 64, 2) hybrid_fwd(Args args) {
;     ...
;             for (int q = 0; q < 4; ++q) { f32x4* orow = (f32x4*)(out + (size_t)(m0 + q) * DM) + lane;
; #pragma unroll
;                 for (int j = 0; j < 8; ++j) { const f32x4 w = wfin[j]; const float s = rs[q];
;                     orow[64 * j] = (f32x4){__uint_as_float(r[q][j].x << 16) * s * w.x, __uint_as_float(r[q][j].x & 0xffff0000u) * s * w.y, __uint_as_float(r[q][j].y << 16) * s * w.z, __uint_as_float(r[q][j].y & 0xffff0000u) * s * w.w}; } }
	v_permlane16_swap_b32_e32 v72, v76
	v_permlane16_swap_b32_e32 v73, v77
	v_permlane16_swap_b32_e32 v74, v78
	v_permlane16_swap_b32_e32 v75, v79
	v_permlane16_swap_b32_e32 v104, v108
	v_permlane16_swap_b32_e32 v105, v109
	v_permlane16_swap_b32_e32 v106, v110
	v_permlane16_swap_b32_e32 v107, v111
	global_store_dwordx4 v234, v[72:75], s[52:53] offset:0
	global_store_dwordx4 v234, v[76:79], s[52:53] offset:32
	global_store_dwordx4 v234, v[104:107], s[52:53] offset:512
	global_store_dwordx4 v234, v[108:111], s[52:53] offset:544
	s_nop 1
	v_fmamk_f32 v235, v226, 0x3a000000, v231
	v_add_u32_e32 v234, 0x140000, v229
	v_rsq_f32_e32 v235, v235
	s_nop 0
	v_mul_f32_e32 v80, v80, v235
	v_mul_f32_e32 v81, v81, v235
	v_mul_f32_e32 v82, v82, v235
	v_mul_f32_e32 v83, v83, v235
	v_mul_f32_e32 v84, v84, v235
	v_mul_f32_e32 v85, v85, v235
	v_mul_f32_e32 v86, v86, v235
	v_mul_f32_e32 v87, v87, v235
	v_mul_f32_e32 v112, v112, v235
	v_mul_f32_e32 v113, v113, v235
	v_mul_f32_e32 v114, v114, v235
	v_mul_f32_e32 v115, v115, v235
	v_mul_f32_e32 v116, v116, v235
	v_mul_f32_e32 v117, v117, v235
	v_mul_f32_e32 v118, v118, v235
	v_mul_f32_e32 v119, v119, v235
	v_mul_f32_e32 v80, v80, v160
	v_mul_f32_e32 v81, v81, v161
	v_mul_f32_e32 v82, v82, v162
	v_mul_f32_e32 v83, v83, v163
	v_mul_f32_e32 v84, v84, v164
	v_mul_f32_e32 v85, v85, v165
	v_mul_f32_e32 v86, v86, v166
	v_mul_f32_e32 v87, v87, v167
	v_mul_f32_e32 v112, v112, v168
	v_mul_f32_e32 v113, v113, v169
	v_mul_f32_e32 v114, v114, v170
	v_mul_f32_e32 v115, v115, v171
	v_mul_f32_e32 v116, v116, v172
	v_mul_f32_e32 v117, v117, v173
	v_mul_f32_e32 v118, v118, v174
	v_mul_f32_e32 v119, v119, v175
	s_nop 1
	v_permlane16_swap_b32_e32 v80, v84
	v_permlane16_swap_b32_e32 v81, v85
	v_permlane16_swap_b32_e32 v82, v86
	v_permlane16_swap_b32_e32 v83, v87
	v_permlane16_swap_b32_e32 v112, v116
	v_permlane16_swap_b32_e32 v113, v117
	v_permlane16_swap_b32_e32 v114, v118
	v_permlane16_swap_b32_e32 v115, v119
	global_store_dwordx4 v234, v[80:83], s[52:53] offset:0
	global_store_dwordx4 v234, v[84:87], s[52:53] offset:32
	global_store_dwordx4 v234, v[112:115], s[52:53] offset:512
	global_store_dwordx4 v234, v[116:119], s[52:53] offset:544
	s_nop 1
	v_fmamk_f32 v235, v227, 0x3a000000, v231
	v_add_u32_e32 v234, 0x160000, v229
	v_rsq_f32_e32 v235, v235
	s_nop 0
	v_mul_f32_e32 v88, v88, v235
	v_mul_f32_e32 v89, v89, v235
	v_mul_f32_e32 v90, v90, v235
	v_mul_f32_e32 v91, v91, v235
	v_mul_f32_e32 v92, v92, v235
	v_mul_f32_e32 v93, v93, v235
	v_mul_f32_e32 v94, v94, v235
	v_mul_f32_e32 v95, v95, v235
	v_mul_f32_e32 v120, v120, v235
	v_mul_f32_e32 v121, v121, v235
	v_mul_f32_e32 v122, v122, v235
	v_mul_f32_e32 v123, v123, v235
	v_mul_f32_e32 v124, v124, v235
	v_mul_f32_e32 v125, v125, v235
	v_mul_f32_e32 v126, v126, v235
	v_mul_f32_e32 v127, v127, v235
	v_mul_f32_e32 v88, v88, v160
	v_mul_f32_e32 v89, v89, v161
	v_mul_f32_e32 v90, v90, v162
	v_mul_f32_e32 v91, v91, v163
	v_mul_f32_e32 v92, v92, v164
	v_mul_f32_e32 v93, v93, v165
	v_mul_f32_e32 v94, v94, v166
	v_mul_f32_e32 v95, v95, v167
	v_mul_f32_e32 v120, v120, v168
	v_mul_f32_e32 v121, v121, v169
	v_mul_f32_e32 v122, v122, v170
	v_mul_f32_e32 v123, v123, v171
	v_mul_f32_e32 v124, v124, v172
	v_mul_f32_e32 v125, v125, v173
	v_mul_f32_e32 v126, v126, v174
	v_mul_f32_e32 v127, v127, v175
	s_nop 1
	v_permlane16_swap_b32_e32 v88, v92
	v_permlane16_swap_b32_e32 v89, v93
	v_permlane16_swap_b32_e32 v90, v94
	v_permlane16_swap_b32_e32 v91, v95
	v_permlane16_swap_b32_e32 v120, v124
	v_permlane16_swap_b32_e32 v121, v125
	v_permlane16_swap_b32_e32 v122, v126
	v_permlane16_swap_b32_e32 v123, v127
	global_store_dwordx4 v234, v[88:91], s[52:53] offset:0
	global_store_dwordx4 v234, v[92:95], s[52:53] offset:32
	global_store_dwordx4 v234, v[120:123], s[52:53] offset:512
	global_store_dwordx4 v234, v[124:127], s[52:53] offset:544
	s_nop 1
	s_cmp_eq_u32 s19, 0
	s_cbranch_scc1 .Lp6_done
	s_mov_b32 s17, s20
	s_mov_b32 s18, s21
	s_mov_b64 s[22:23], s[26:27]
	s_mov_b64 s[24:25], s[28:29]
	s_add_u32 s16, s16, 1
	s_branch .Lp6_unit
